# down GEMM of every layer runs 2 rounds + split-K tail (the last layer's path); workgroups without a tail unit convert the next layer's weights beside it
# speedup vs baseline: 1.0192x; 1.0192x over previous
; #define LAS __attribute__((address_space(3)))
; #define FRESH_TID() int tid = threadIdx.x; asm volatile("" : "+v"(tid)); const int lane = tid & 63, wave = __builtin_amdgcn_readfirstlane(tid >> 6); (void)lane; (void)wave
; __device__ __forceinline__ void convert_layer(const Args& a, unsigned char* ws, LAS unsigned char* lds, int l, int worker, int nworkers, int wave, int lane, int it_lo, int it_hi) {
;     LAS float* scr = (LAS float*)(lds + wave * 16384);
;     constexpr int I_IN = 32 * 192, I_OUT = 32 * 64, I_G = 32 * 176, I_D = 88 * 64, I_LAYER = I_IN + I_OUT + 2 * I_G + I_D;
;     unsigned char* wl = ws + WS_WT + (size_t)l * WT_LAYER;
;     for (int it = it_lo + worker; it < it_hi; it += nworkers) {
;         int rr = it;
; __global__ void __launch_bounds__(512, 2) hymba_fwd(Args a) {
;     ...
;             if (l + 1 < DEPTH) {
;                 pg8::gemm_phase<pg8::EpiResidual<false>, pg8::StaticOrder, true, true>(lds, g, S, E);
;                 if (bx >= 16) { FRESH_TID(); convert_layer(a, ws, lds, l + 1, (bx - 16) * 8 + wave, (G - 16) * 8, wave, lane, 0, CV_ALL); }
;             } else {
;                 S.limit = 2 * 256;
;                 pg8::gemm_phase<pg8::EpiResidual<false>, pg8::StaticOrder, true, true>(lds, g, S, E);
;                 pg8::Gemm gt{actbuf, (const bf16_t*)(wl + WT_DOWN), MT, DM, DFF / 4, DFF}; const pg8::TailOrder T{MT / 256, DM / 256, 2 * 256, 16, bx};
;                 pg8::EpiSplitK<pg8::EpiResidual<false>> Et{E, (float*)(ws + WS_R + R_G), ctl + 2048 + l * 256 + 128};
;                 pg8::gemm_phase<pg8::EpiSplitK<pg8::EpiResidual<false>>, pg8::TailOrder, true, true>(lds, gt, T, Et);
;             }
.LBB0_866:
	s_or_b64 exec, exec, s[14:15]
	v_readlane_b32 s0, v253, 50
	s_add_u32 s26, s0, 0x4c00000
	v_readlane_b32 s0, v253, 47
	s_addc_u32 s27, s0, 0
	v_readlane_b32 s0, v253, 57
	s_add_i32 s48, s0, 1
	s_cmp_lg_u32 s0, 3
	s_mov_b64 s[14:15], -1
	s_waitcnt lgkmcnt(0)
	s_barrier
	s_branch .LBB0_984
.Lcv_tail:
	v_readlane_b32 s0, v253, 57
	s_cmp_eq_u32 s0, 3
	s_cbranch_scc1 .LBB0_1085
	s_add_i32 s48, s0, 1
	v_mov_b32_e32 v12, v208
	s_nop 0
	v_readfirstlane_b32 s0, v12
	s_ashr_i32 s2, s0, 6
	v_readlane_b32 s0, v254, 45
	s_addk_i32 s0, 0xfe80
	s_add_i32 s0, s0, s2
	s_cmpk_gt_i32 s0, 0x61ff
	s_cbranch_scc1 .LBB0_983
	s_mul_i32 s3, s48, 0x6200000
	v_readlane_b32 s10, v253, 39
	v_lshlrev_b32_e32 v0, 3, v12
	s_mul_hi_u32 s1, s48, 0x6200000
	v_readlane_b32 s11, v253, 40
	s_add_u32 s10, s10, s3
	v_and_b32_e32 v0, 56, v0
	s_addc_u32 s11, s11, s1
	v_mul_u32_u24_e32 v8, 0x84, v0
	v_lshlrev_b32_e32 v0, 1, v0
	s_lshl_b32 s1, s2, 14
	s_waitcnt lgkmcnt(0)
	v_bfe_u32 v3, v12, 3, 3
	v_lshl_add_u64 v[4:5], s[10:11], 0, v[0:1]
	s_mov_b64 s[10:11], 0x4c00000
	s_add_i32 s3, s1, 0
	v_bfe_u32 v2, v12, 5, 1
	v_lshl_add_u64 v[6:7], v[4:5], 0, s[10:11]
	v_lshlrev_b32_e32 v0, 2, v3
	s_mov_b64 s[10:11], 0x2000000
	v_add3_u32 v44, s3, v8, v0
	v_lshl_add_u64 v[8:9], v[4:5], 0, s[10:11]
	s_mov_b64 s[10:11], 0x1800000
	v_mul_u32_u24_e32 v0, 0x84, v2
	v_lshl_add_u64 v[10:11], v[4:5], 0, s[10:11]
	v_or_b32_e32 v13, s1, v0
	v_lshlrev_b32_e32 v0, 2, v12
	v_readlane_b32 s10, v255, 38
	v_and_b32_e32 v0, 0x7c, v0
	v_readlane_b32 s11, v255, 39
	v_add3_u32 v48, v13, v0, 0
	s_waitcnt vmcnt(0)
	v_lshlrev_b32_e32 v16, 2, v2
	v_lshl_add_u64 v[12:13], s[10:11], 0, v[0:1]
	v_readlane_b32 s10, v255, 41
	v_readlane_b32 s11, v255, 42
	v_mov_b32_e32 v17, v1
	v_readlane_b32 s3, v255, 52
	s_addk_i32 s3, 0xfe80
	v_lshl_add_u64 v[14:15], s[10:11], 0, v[0:1]
	v_readlane_b32 s10, v255, 45
	v_readlane_b32 s11, v255, 46
	v_or_b32_e32 v45, 8, v3
	v_or_b32_e32 v46, 16, v3
	v_lshl_add_u64 v[16:17], s[10:11], 0, v[16:17]
	v_readlane_b32 s10, v255, 47
	v_readlane_b32 s11, v255, 48
	v_or_b32_e32 v47, 24, v3
	v_or_b32_e32 v49, 0xffffb40e, v2
	v_lshl_add_u64 v[18:19], s[10:11], 0, v[0:1]
	v_readlane_b32 s10, v255, 49
	v_readlane_b32 s11, v255, 50
	s_lshl_b32 s1, s0, 5
	v_or_b32_e32 v50, 0xffffb40c, v2
	v_lshl_add_u64 v[20:21], s[10:11], 0, v[0:1]
	v_readlane_b32 s10, v255, 53
	v_readlane_b32 s11, v255, 54
	v_or_b32_e32 v51, 0xffffb40a, v2
	v_or_b32_e32 v52, 0xffffb408, v2
	v_or_b32_e32 v53, 0xffffb406, v2
	v_or_b32_e32 v54, 0xffffb404, v2
	v_or_b32_e32 v55, 0xffffb402, v2
	v_or_b32_e32 v56, 0xffffb400, v2
	v_or_b32_e32 v57, 14, v2
	v_or_b32_e32 v58, 12, v2
	v_or_b32_e32 v59, 10, v2
	v_or_b32_e32 v60, 8, v2
	v_or_b32_e32 v61, 2, v2
	v_or_b32_e32 v62, 6, v2
	v_or_b32_e32 v63, 4, v2
	s_add_i32 s2, s3, s2
	v_lshl_add_u64 v[22:23], s[10:11], 0, v[0:1]
	s_mov_b32 s3, s0
	s_branch .LBB0_910

; #define LAS __attribute__((address_space(3)))
; __device__ __forceinline__ void convert_layer(const Args& a, unsigned char* ws, LAS unsigned char* lds, int l, int worker, int nworkers, int wave, int lane, int it_lo, int it_hi) {
;     LAS float* scr = (LAS float*)(lds + wave * 16384);
;     constexpr int I_IN = 32 * 192, I_OUT = 32 * 64, I_G = 32 * 176, I_D = 88 * 64, I_LAYER = I_IN + I_OUT + 2 * I_G + I_D;
;     unsigned char* wl = ws + WS_WT + (size_t)l * WT_LAYER;
;     for (int it = it_lo + worker; it < it_hi; it += nworkers) {
;         int rr = it;
.LBB0_909:
	v_readlane_b32 s8, v254, 47
	s_addk_i32 s8, 0xfe80
	v_readlane_b32 s10, v255, 40
	s_addk_i32 s10, 0xd000
	s_add_i32 s3, s8, s3
	s_add_i32 s0, s0, s8
	s_add_i32 s1, s1, s10
	s_add_i32 s2, s2, s8
	s_cmpk_gt_i32 s3, 0x61ff
	s_cbranch_scc1 .LBB0_983
